# grid barrier: 32 generation words at 64 B stride (8 pollers per word), poll loop without s_sleep
# speedup vs baseline: 1.0020x; 1.0020x over previous
; __device__ __forceinline__ void grid_barrier(unsigned* bar, unsigned& epoch) {
;     ...
;         const unsigned old = __hip_atomic_fetch_add(bar, 1u, __ATOMIC_RELAXED, __HIP_MEMORY_SCOPE_AGENT);
;         if (old + 1u == epoch * gridDim.x) {
;             __hip_atomic_store(bar + 64, epoch, __ATOMIC_RELAXED, __HIP_MEMORY_SCOPE_AGENT);
;         } else {
;             while (__hip_atomic_load(bar + 64, __ATOMIC_RELAXED, __HIP_MEMORY_SCOPE_AGENT) < epoch) __builtin_amdgcn_s_sleep(1);
;         }
.LBB0_276:
	s_or_b64 exec, exec, s[4:5]
	s_waitcnt vmcnt(0)
	v_readfirstlane_b32 s2, v1
	s_nop 1
	v_add3_u32 v0, s2, v0, 1
	v_cmp_ne_u32_e32 vcc, s45, v0
	s_and_saveexec_b64 s[2:3], vcc
	s_xor_b64 s[2:3], exec, s[2:3]
	s_cbranch_execz .LBB0_279
	v_mov_b32_e32 v0, 0
	v_readlane_b32 vcc_lo, v253, 0
	s_and_b32 vcc_lo, vcc_lo, 31
	s_lshl_b32 vcc_lo, vcc_lo, 6
	s_addk_i32 vcc_lo, 0x1400
	v_mov_b32_e32 v0, vcc_lo
	global_load_dword v1, v0, s[30:31] sc1
	s_waitcnt vmcnt(0)
	v_cmp_ne_u32_e32 vcc, 0, v1
	s_cbranch_vccnz .LBB0_279
.LBB0_278:
	global_load_dword v1, v0, s[30:31] sc1
	s_waitcnt vmcnt(0)
	v_cmp_eq_u32_e32 vcc, 0, v1
	s_cbranch_vccnz .LBB0_278
.LBB0_279:
	s_andn2_saveexec_b64 s[2:3], s[2:3]
	s_cbranch_execz .LBB0_281
	v_mov_b32_e32 v0, 0
	v_mov_b32_e32 v1, 1
	v_mov_b32_e32 v0, 0x1400
	global_store_dword v0, v1, s[30:31] sc1
	global_store_dword v0, v1, s[30:31] offset:64 sc1
	global_store_dword v0, v1, s[30:31] offset:128 sc1
	global_store_dword v0, v1, s[30:31] offset:192 sc1
	global_store_dword v0, v1, s[30:31] offset:256 sc1
	global_store_dword v0, v1, s[30:31] offset:320 sc1
	global_store_dword v0, v1, s[30:31] offset:384 sc1
	global_store_dword v0, v1, s[30:31] offset:448 sc1
	global_store_dword v0, v1, s[30:31] offset:512 sc1
	global_store_dword v0, v1, s[30:31] offset:576 sc1
	global_store_dword v0, v1, s[30:31] offset:640 sc1
	global_store_dword v0, v1, s[30:31] offset:704 sc1
	global_store_dword v0, v1, s[30:31] offset:768 sc1
	global_store_dword v0, v1, s[30:31] offset:832 sc1
	global_store_dword v0, v1, s[30:31] offset:896 sc1
	global_store_dword v0, v1, s[30:31] offset:960 sc1
	global_store_dword v0, v1, s[30:31] offset:1024 sc1
	global_store_dword v0, v1, s[30:31] offset:1088 sc1
	global_store_dword v0, v1, s[30:31] offset:1152 sc1
	global_store_dword v0, v1, s[30:31] offset:1216 sc1
	global_store_dword v0, v1, s[30:31] offset:1280 sc1
	global_store_dword v0, v1, s[30:31] offset:1344 sc1
	global_store_dword v0, v1, s[30:31] offset:1408 sc1
	global_store_dword v0, v1, s[30:31] offset:1472 sc1
	global_store_dword v0, v1, s[30:31] offset:1536 sc1
	global_store_dword v0, v1, s[30:31] offset:1600 sc1
	global_store_dword v0, v1, s[30:31] offset:1664 sc1
	global_store_dword v0, v1, s[30:31] offset:1728 sc1
	global_store_dword v0, v1, s[30:31] offset:1792 sc1
	global_store_dword v0, v1, s[30:31] offset:1856 sc1
	global_store_dword v0, v1, s[30:31] offset:1920 sc1
	global_store_dword v0, v1, s[30:31] offset:1984 sc1

; __device__ __forceinline__ void grid_barrier(unsigned* bar, unsigned& epoch) {
;     ...
;         const unsigned old = __hip_atomic_fetch_add(bar, 1u, __ATOMIC_RELAXED, __HIP_MEMORY_SCOPE_AGENT);
;         if (old + 1u == epoch * gridDim.x) {
;             __hip_atomic_store(bar + 64, epoch, __ATOMIC_RELAXED, __HIP_MEMORY_SCOPE_AGENT);
;         } else {
;             while (__hip_atomic_load(bar + 64, __ATOMIC_RELAXED, __HIP_MEMORY_SCOPE_AGENT) < epoch) __builtin_amdgcn_s_sleep(1);
;         }
.LBB0_292:
	s_or_b64 exec, exec, s[4:5]
	s_waitcnt vmcnt(0)
	v_readfirstlane_b32 s2, v1
	s_nop 1
	v_add3_u32 v0, s2, v0, 1
	s_lshl_b32 s2, s45, 1
	v_cmp_ne_u32_e32 vcc, s2, v0
	s_and_saveexec_b64 s[2:3], vcc
	s_xor_b64 s[2:3], exec, s[2:3]
	s_cbranch_execz .LBB0_295
	v_mov_b32_e32 v0, 0
	v_readlane_b32 vcc_lo, v253, 0
	s_and_b32 vcc_lo, vcc_lo, 31
	s_lshl_b32 vcc_lo, vcc_lo, 6
	s_addk_i32 vcc_lo, 0x1400
	v_mov_b32_e32 v0, vcc_lo
	global_load_dword v1, v0, s[30:31] sc1
	s_waitcnt vmcnt(0)
	v_cmp_lt_u32_e32 vcc, 1, v1
	s_cbranch_vccnz .LBB0_295
.LBB0_294:
	global_load_dword v1, v0, s[30:31] sc1
	s_waitcnt vmcnt(0)
	v_cmp_gt_u32_e32 vcc, 2, v1
	s_cbranch_vccnz .LBB0_294
.LBB0_295:
	s_andn2_saveexec_b64 s[2:3], s[2:3]
	s_cbranch_execz .LBB0_297
	v_mov_b32_e32 v0, 0
	v_mov_b32_e32 v1, 2
	v_mov_b32_e32 v0, 0x1400
	global_store_dword v0, v1, s[30:31] sc1
	global_store_dword v0, v1, s[30:31] offset:64 sc1
	global_store_dword v0, v1, s[30:31] offset:128 sc1
	global_store_dword v0, v1, s[30:31] offset:192 sc1
	global_store_dword v0, v1, s[30:31] offset:256 sc1
	global_store_dword v0, v1, s[30:31] offset:320 sc1
	global_store_dword v0, v1, s[30:31] offset:384 sc1
	global_store_dword v0, v1, s[30:31] offset:448 sc1
	global_store_dword v0, v1, s[30:31] offset:512 sc1
	global_store_dword v0, v1, s[30:31] offset:576 sc1
	global_store_dword v0, v1, s[30:31] offset:640 sc1
	global_store_dword v0, v1, s[30:31] offset:704 sc1
	global_store_dword v0, v1, s[30:31] offset:768 sc1
	global_store_dword v0, v1, s[30:31] offset:832 sc1
	global_store_dword v0, v1, s[30:31] offset:896 sc1
	global_store_dword v0, v1, s[30:31] offset:960 sc1
	global_store_dword v0, v1, s[30:31] offset:1024 sc1
	global_store_dword v0, v1, s[30:31] offset:1088 sc1
	global_store_dword v0, v1, s[30:31] offset:1152 sc1
	global_store_dword v0, v1, s[30:31] offset:1216 sc1
	global_store_dword v0, v1, s[30:31] offset:1280 sc1
	global_store_dword v0, v1, s[30:31] offset:1344 sc1
	global_store_dword v0, v1, s[30:31] offset:1408 sc1
	global_store_dword v0, v1, s[30:31] offset:1472 sc1
	global_store_dword v0, v1, s[30:31] offset:1536 sc1
	global_store_dword v0, v1, s[30:31] offset:1600 sc1
	global_store_dword v0, v1, s[30:31] offset:1664 sc1
	global_store_dword v0, v1, s[30:31] offset:1728 sc1
	global_store_dword v0, v1, s[30:31] offset:1792 sc1
	global_store_dword v0, v1, s[30:31] offset:1856 sc1
	global_store_dword v0, v1, s[30:31] offset:1920 sc1
	global_store_dword v0, v1, s[30:31] offset:1984 sc1

; __device__ __forceinline__ void grid_barrier(unsigned* bar, unsigned& epoch) {
;     ...
;         const unsigned old = __hip_atomic_fetch_add(bar, 1u, __ATOMIC_RELAXED, __HIP_MEMORY_SCOPE_AGENT);
;         if (old + 1u == epoch * gridDim.x) {
;             __hip_atomic_store(bar + 64, epoch, __ATOMIC_RELAXED, __HIP_MEMORY_SCOPE_AGENT);
;         } else {
;             while (__hip_atomic_load(bar + 64, __ATOMIC_RELAXED, __HIP_MEMORY_SCOPE_AGENT) < epoch) __builtin_amdgcn_s_sleep(1);
;         }
.LBB0_368:
	s_or_b64 exec, exec, s[6:7]
	s_add_i32 s6, s82, 1
	s_waitcnt vmcnt(0)
	v_readfirstlane_b32 s4, v1
	s_nop 1
	v_add3_u32 v0, s4, v0, 1
	s_mul_i32 s4, s6, s45
	v_cmp_ne_u32_e32 vcc, s4, v0
	s_and_saveexec_b64 s[4:5], vcc
	v_readlane_b32 s22, v254, 35
	s_xor_b64 s[4:5], exec, s[4:5]
	v_readlane_b32 s23, v254, 36
	s_cbranch_execz .LBB0_371
	s_nop 3
	v_readlane_b32 vcc_lo, v253, 0
	s_and_b32 vcc_lo, vcc_lo, 31
	s_lshl_b32 vcc_lo, vcc_lo, 6
	s_addk_i32 vcc_lo, 0x1400
	v_mov_b32_e32 v1, vcc_lo
	global_load_dword v0, v1, s[22:23] sc1
	s_waitcnt vmcnt(0)
	v_cmp_le_u32_e32 vcc, s6, v0
	s_cbranch_vccnz .LBB0_371
.LBB0_370:
	global_load_dword v0, v1, s[22:23] sc1
	s_waitcnt vmcnt(0)
	v_cmp_gt_u32_e32 vcc, s6, v0
	s_cbranch_vccnz .LBB0_370
.LBB0_371:
	s_andn2_saveexec_b64 s[4:5], s[4:5]
	s_cbranch_execz .LBB0_373
	v_mov_b32_e32 v0, s6
	v_readlane_b32 s6, v254, 35
	v_readlane_b32 s7, v254, 36
	s_nop 4
	v_mov_b32_e32 v1, 0x1400
	global_store_dword v1, v0, s[6:7] sc1
	global_store_dword v1, v0, s[6:7] offset:64 sc1
	global_store_dword v1, v0, s[6:7] offset:128 sc1
	global_store_dword v1, v0, s[6:7] offset:192 sc1
	global_store_dword v1, v0, s[6:7] offset:256 sc1
	global_store_dword v1, v0, s[6:7] offset:320 sc1
	global_store_dword v1, v0, s[6:7] offset:384 sc1
	global_store_dword v1, v0, s[6:7] offset:448 sc1
	global_store_dword v1, v0, s[6:7] offset:512 sc1
	global_store_dword v1, v0, s[6:7] offset:576 sc1
	global_store_dword v1, v0, s[6:7] offset:640 sc1
	global_store_dword v1, v0, s[6:7] offset:704 sc1
	global_store_dword v1, v0, s[6:7] offset:768 sc1
	global_store_dword v1, v0, s[6:7] offset:832 sc1
	global_store_dword v1, v0, s[6:7] offset:896 sc1
	global_store_dword v1, v0, s[6:7] offset:960 sc1
	global_store_dword v1, v0, s[6:7] offset:1024 sc1
	global_store_dword v1, v0, s[6:7] offset:1088 sc1
	global_store_dword v1, v0, s[6:7] offset:1152 sc1
	global_store_dword v1, v0, s[6:7] offset:1216 sc1
	global_store_dword v1, v0, s[6:7] offset:1280 sc1
	global_store_dword v1, v0, s[6:7] offset:1344 sc1
	global_store_dword v1, v0, s[6:7] offset:1408 sc1
	global_store_dword v1, v0, s[6:7] offset:1472 sc1
	global_store_dword v1, v0, s[6:7] offset:1536 sc1
	global_store_dword v1, v0, s[6:7] offset:1600 sc1
	global_store_dword v1, v0, s[6:7] offset:1664 sc1
	global_store_dword v1, v0, s[6:7] offset:1728 sc1
	global_store_dword v1, v0, s[6:7] offset:1792 sc1
	global_store_dword v1, v0, s[6:7] offset:1856 sc1
	global_store_dword v1, v0, s[6:7] offset:1920 sc1
	global_store_dword v1, v0, s[6:7] offset:1984 sc1

; __device__ __forceinline__ void grid_barrier(unsigned* bar, unsigned& epoch) {
;     ...
;         const unsigned old = __hip_atomic_fetch_add(bar, 1u, __ATOMIC_RELAXED, __HIP_MEMORY_SCOPE_AGENT);
;         if (old + 1u == epoch * gridDim.x) {
;             __hip_atomic_store(bar + 64, epoch, __ATOMIC_RELAXED, __HIP_MEMORY_SCOPE_AGENT);
;         } else {
;             while (__hip_atomic_load(bar + 64, __ATOMIC_RELAXED, __HIP_MEMORY_SCOPE_AGENT) < epoch) __builtin_amdgcn_s_sleep(1);
;         }
.LBB0_389:
	s_or_b64 exec, exec, s[6:7]
	s_add_i32 s6, s82, 2
	s_waitcnt vmcnt(0)
	v_readfirstlane_b32 s4, v1
	s_nop 1
	v_add3_u32 v0, s4, v0, 1
	s_mul_i32 s4, s6, s45
	v_cmp_ne_u32_e32 vcc, s4, v0
	s_and_saveexec_b64 s[4:5], vcc
	v_readlane_b32 s22, v254, 35
	s_xor_b64 s[4:5], exec, s[4:5]
	v_readlane_b32 s23, v254, 36
	s_cbranch_execz .LBB0_392
	s_nop 3
	v_readlane_b32 vcc_lo, v253, 0
	s_and_b32 vcc_lo, vcc_lo, 31
	s_lshl_b32 vcc_lo, vcc_lo, 6
	s_addk_i32 vcc_lo, 0x1400
	v_mov_b32_e32 v1, vcc_lo
	global_load_dword v0, v1, s[22:23] sc1
	s_waitcnt vmcnt(0)
	v_cmp_le_u32_e32 vcc, s6, v0
	s_cbranch_vccnz .LBB0_392

; __device__ __forceinline__ void grid_barrier(unsigned* bar, unsigned& epoch) {
;     ...
;         const unsigned old = __hip_atomic_fetch_add(bar, 1u, __ATOMIC_RELAXED, __HIP_MEMORY_SCOPE_AGENT);
;         if (old + 1u == epoch * gridDim.x) {
;             __hip_atomic_store(bar + 64, epoch, __ATOMIC_RELAXED, __HIP_MEMORY_SCOPE_AGENT);
;         } else {
;             while (__hip_atomic_load(bar + 64, __ATOMIC_RELAXED, __HIP_MEMORY_SCOPE_AGENT) < epoch) __builtin_amdgcn_s_sleep(1);
;         }
.LBB0_507:
	s_or_b64 exec, exec, s[6:7]
	s_add_i32 s6, s82, 3
	s_waitcnt vmcnt(0)
	v_readfirstlane_b32 s4, v1
	s_nop 1
	v_add3_u32 v0, s4, v0, 1
	s_mul_i32 s4, s6, s45
	v_cmp_ne_u32_e32 vcc, s4, v0
	s_and_saveexec_b64 s[4:5], vcc
	v_readlane_b32 s22, v254, 35
	s_xor_b64 s[4:5], exec, s[4:5]
	v_readlane_b32 s23, v254, 36
	s_cbranch_execz .LBB0_510
	s_nop 3
	v_readlane_b32 vcc_lo, v253, 0
	s_and_b32 vcc_lo, vcc_lo, 31
	s_lshl_b32 vcc_lo, vcc_lo, 6
	s_addk_i32 vcc_lo, 0x1400
	v_mov_b32_e32 v1, vcc_lo
	global_load_dword v0, v1, s[22:23] sc1
	s_waitcnt vmcnt(0)
	v_cmp_le_u32_e32 vcc, s6, v0
	s_cbranch_vccnz .LBB0_510

; __device__ __forceinline__ void grid_barrier(unsigned* bar, unsigned& epoch) {
;     ...
;         const unsigned old = __hip_atomic_fetch_add(bar, 1u, __ATOMIC_RELAXED, __HIP_MEMORY_SCOPE_AGENT);
;         if (old + 1u == epoch * gridDim.x) {
;             __hip_atomic_store(bar + 64, epoch, __ATOMIC_RELAXED, __HIP_MEMORY_SCOPE_AGENT);
;         } else {
;             while (__hip_atomic_load(bar + 64, __ATOMIC_RELAXED, __HIP_MEMORY_SCOPE_AGENT) < epoch) __builtin_amdgcn_s_sleep(1);
;         }
.LBB0_639:
	s_or_b64 exec, exec, s[6:7]
	s_add_i32 s6, s82, 4
	s_waitcnt vmcnt(0)
	v_readfirstlane_b32 s4, v1
	s_nop 1
	v_add3_u32 v0, s4, v0, 1
	s_mul_i32 s4, s6, s45
	v_cmp_ne_u32_e32 vcc, s4, v0
	s_and_saveexec_b64 s[4:5], vcc
	v_readlane_b32 s22, v254, 35
	s_xor_b64 s[4:5], exec, s[4:5]
	v_readlane_b32 s23, v254, 36
	s_cbranch_execz .LBB0_642
	s_nop 3
	v_readlane_b32 vcc_lo, v253, 0
	s_and_b32 vcc_lo, vcc_lo, 31
	s_lshl_b32 vcc_lo, vcc_lo, 6
	s_addk_i32 vcc_lo, 0x1400
	v_mov_b32_e32 v1, vcc_lo
	global_load_dword v0, v1, s[22:23] sc1
	s_waitcnt vmcnt(0)
	v_cmp_le_u32_e32 vcc, s6, v0
	s_cbranch_vccnz .LBB0_642

; __device__ __forceinline__ void grid_barrier(unsigned* bar, unsigned& epoch) {
;     ...
;         const unsigned old = __hip_atomic_fetch_add(bar, 1u, __ATOMIC_RELAXED, __HIP_MEMORY_SCOPE_AGENT);
;         if (old + 1u == epoch * gridDim.x) {
;             __hip_atomic_store(bar + 64, epoch, __ATOMIC_RELAXED, __HIP_MEMORY_SCOPE_AGENT);
;         } else {
;             while (__hip_atomic_load(bar + 64, __ATOMIC_RELAXED, __HIP_MEMORY_SCOPE_AGENT) < epoch) __builtin_amdgcn_s_sleep(1);
;         }
.LBB0_671:
	s_or_b64 exec, exec, s[6:7]
	s_add_i32 s6, s82, 5
	s_waitcnt vmcnt(0)
	v_readfirstlane_b32 s4, v1
	s_nop 1
	v_add3_u32 v0, s4, v0, 1
	s_mul_i32 s4, s6, s45
	v_cmp_ne_u32_e32 vcc, s4, v0
	s_and_saveexec_b64 s[4:5], vcc
	v_readlane_b32 s42, v254, 35
	s_xor_b64 s[4:5], exec, s[4:5]
	v_readlane_b32 s43, v254, 36
	s_cbranch_execz .LBB0_674
	s_nop 3
	v_readlane_b32 vcc_lo, v253, 0
	s_and_b32 vcc_lo, vcc_lo, 31
	s_lshl_b32 vcc_lo, vcc_lo, 6
	s_addk_i32 vcc_lo, 0x1400
	v_mov_b32_e32 v1, vcc_lo
	global_load_dword v0, v1, s[42:43] sc1
	s_waitcnt vmcnt(0)
	v_cmp_le_u32_e32 vcc, s6, v0
	s_cbranch_vccnz .LBB0_674
.LBB0_673:
	global_load_dword v0, v1, s[42:43] sc1
	s_waitcnt vmcnt(0)
	v_cmp_gt_u32_e32 vcc, s6, v0
	s_cbranch_vccnz .LBB0_673

; __device__ __forceinline__ void grid_barrier(unsigned* bar, unsigned& epoch) {
;     ...
;         const unsigned old = __hip_atomic_fetch_add(bar, 1u, __ATOMIC_RELAXED, __HIP_MEMORY_SCOPE_AGENT);
;         if (old + 1u == epoch * gridDim.x) {
;             __hip_atomic_store(bar + 64, epoch, __ATOMIC_RELAXED, __HIP_MEMORY_SCOPE_AGENT);
;         } else {
;             while (__hip_atomic_load(bar + 64, __ATOMIC_RELAXED, __HIP_MEMORY_SCOPE_AGENT) < epoch) __builtin_amdgcn_s_sleep(1);
;         }
.LBB0_725:
	s_or_b64 exec, exec, s[6:7]
	s_add_i32 s6, s82, 6
	s_waitcnt vmcnt(0)
	v_readfirstlane_b32 s4, v1
	s_nop 1
	v_add3_u32 v0, s4, v0, 1
	s_mul_i32 s4, s6, s45
	v_cmp_ne_u32_e32 vcc, s4, v0
	s_and_saveexec_b64 s[4:5], vcc
	v_readlane_b32 s42, v254, 35
	s_xor_b64 s[4:5], exec, s[4:5]
	v_readlane_b32 s43, v254, 36
	s_cbranch_execz .LBB0_728
	s_nop 3
	v_readlane_b32 vcc_lo, v253, 0
	s_and_b32 vcc_lo, vcc_lo, 31
	s_lshl_b32 vcc_lo, vcc_lo, 6
	s_addk_i32 vcc_lo, 0x1400
	v_mov_b32_e32 v1, vcc_lo
	global_load_dword v0, v1, s[42:43] sc1
	s_waitcnt vmcnt(0)
	v_cmp_le_u32_e32 vcc, s6, v0
	s_cbranch_vccnz .LBB0_728

; __device__ __forceinline__ void grid_barrier(unsigned* bar, unsigned& epoch) {
;     ...
;         const unsigned old = __hip_atomic_fetch_add(bar, 1u, __ATOMIC_RELAXED, __HIP_MEMORY_SCOPE_AGENT);
;         if (old + 1u == epoch * gridDim.x) {
;             __hip_atomic_store(bar + 64, epoch, __ATOMIC_RELAXED, __HIP_MEMORY_SCOPE_AGENT);
;         } else {
;             while (__hip_atomic_load(bar + 64, __ATOMIC_RELAXED, __HIP_MEMORY_SCOPE_AGENT) < epoch) __builtin_amdgcn_s_sleep(1);
;         }
.LBB0_993:
	s_or_b64 exec, exec, s[6:7]
	s_add_i32 s6, s82, 7
	s_waitcnt vmcnt(0)
	v_readfirstlane_b32 s4, v1
	s_nop 1
	v_add3_u32 v0, s4, v0, 1
	s_mul_i32 s4, s6, s45
	v_cmp_ne_u32_e32 vcc, s4, v0
	s_and_saveexec_b64 s[4:5], vcc
	v_readlane_b32 s42, v254, 35
	s_xor_b64 s[4:5], exec, s[4:5]
	v_readlane_b32 s43, v254, 36
	s_cbranch_execz .LBB0_996
	s_nop 3
	v_readlane_b32 vcc_lo, v253, 0
	s_and_b32 vcc_lo, vcc_lo, 31
	s_lshl_b32 vcc_lo, vcc_lo, 6
	s_addk_i32 vcc_lo, 0x1400
	v_mov_b32_e32 v1, vcc_lo
	global_load_dword v0, v1, s[42:43] sc1
	s_waitcnt vmcnt(0)
	v_cmp_le_u32_e32 vcc, s6, v0
	s_cbranch_vccnz .LBB0_996

; __device__ __forceinline__ void grid_barrier(unsigned* bar, unsigned& epoch) {
;     ...
;         const unsigned old = __hip_atomic_fetch_add(bar, 1u, __ATOMIC_RELAXED, __HIP_MEMORY_SCOPE_AGENT);
;         if (old + 1u == epoch * gridDim.x) {
;             __hip_atomic_store(bar + 64, epoch, __ATOMIC_RELAXED, __HIP_MEMORY_SCOPE_AGENT);
;         } else {
;             while (__hip_atomic_load(bar + 64, __ATOMIC_RELAXED, __HIP_MEMORY_SCOPE_AGENT) < epoch) __builtin_amdgcn_s_sleep(1);
;         }
.LBB0_1007:
	s_or_b64 exec, exec, s[48:49]
	s_add_i32 s2, s82, 8
	s_waitcnt vmcnt(0)
	v_readfirstlane_b32 s3, v1
	s_nop 1
	v_add3_u32 v0, s3, v0, 1
	s_mul_i32 s3, s2, s45
	v_cmp_ne_u32_e32 vcc, s3, v0
	s_and_saveexec_b64 s[38:39], vcc
	s_xor_b64 s[46:47], exec, s[38:39]
	v_readlane_b32 s38, v254, 35
	v_readlane_b32 s39, v254, 36
	s_cbranch_execz .LBB0_1010
	s_nop 3
	v_readlane_b32 vcc_lo, v253, 0
	s_and_b32 vcc_lo, vcc_lo, 31
	s_lshl_b32 vcc_lo, vcc_lo, 6
	s_addk_i32 vcc_lo, 0x1400
	v_mov_b32_e32 v1, vcc_lo
	global_load_dword v0, v1, s[38:39] sc1
	s_waitcnt vmcnt(0)
	v_cmp_le_u32_e32 vcc, s2, v0
	s_cbranch_vccnz .LBB0_1010
.LBB0_1009:
	global_load_dword v0, v1, s[38:39] sc1
	s_waitcnt vmcnt(0)
	v_cmp_gt_u32_e32 vcc, s2, v0
	s_cbranch_vccnz .LBB0_1009
.LBB0_1010:
	s_andn2_saveexec_b64 s[46:47], s[46:47]
	s_cbranch_execz .LBB0_1012
	v_mov_b32_e32 v0, s2
	v_readlane_b32 s2, v254, 35
	v_readlane_b32 s3, v254, 36
	s_nop 4
	v_mov_b32_e32 v1, 0x1400
	global_store_dword v1, v0, s[2:3] sc1
	global_store_dword v1, v0, s[2:3] offset:64 sc1
	global_store_dword v1, v0, s[2:3] offset:128 sc1
	global_store_dword v1, v0, s[2:3] offset:192 sc1
	global_store_dword v1, v0, s[2:3] offset:256 sc1
	global_store_dword v1, v0, s[2:3] offset:320 sc1
	global_store_dword v1, v0, s[2:3] offset:384 sc1
	global_store_dword v1, v0, s[2:3] offset:448 sc1
	global_store_dword v1, v0, s[2:3] offset:512 sc1
	global_store_dword v1, v0, s[2:3] offset:576 sc1
	global_store_dword v1, v0, s[2:3] offset:640 sc1
	global_store_dword v1, v0, s[2:3] offset:704 sc1
	global_store_dword v1, v0, s[2:3] offset:768 sc1
	global_store_dword v1, v0, s[2:3] offset:832 sc1
	global_store_dword v1, v0, s[2:3] offset:896 sc1
	global_store_dword v1, v0, s[2:3] offset:960 sc1
	global_store_dword v1, v0, s[2:3] offset:1024 sc1
	global_store_dword v1, v0, s[2:3] offset:1088 sc1
	global_store_dword v1, v0, s[2:3] offset:1152 sc1
	global_store_dword v1, v0, s[2:3] offset:1216 sc1
	global_store_dword v1, v0, s[2:3] offset:1280 sc1
	global_store_dword v1, v0, s[2:3] offset:1344 sc1
	global_store_dword v1, v0, s[2:3] offset:1408 sc1
	global_store_dword v1, v0, s[2:3] offset:1472 sc1
	global_store_dword v1, v0, s[2:3] offset:1536 sc1
	global_store_dword v1, v0, s[2:3] offset:1600 sc1
	global_store_dword v1, v0, s[2:3] offset:1664 sc1
	global_store_dword v1, v0, s[2:3] offset:1728 sc1
	global_store_dword v1, v0, s[2:3] offset:1792 sc1
	global_store_dword v1, v0, s[2:3] offset:1856 sc1
	global_store_dword v1, v0, s[2:3] offset:1920 sc1
	global_store_dword v1, v0, s[2:3] offset:1984 sc1

; __device__ __forceinline__ void grid_barrier(unsigned* bar, unsigned& epoch) {
;     ...
;         const unsigned old = __hip_atomic_fetch_add(bar, 1u, __ATOMIC_RELAXED, __HIP_MEMORY_SCOPE_AGENT);
;         if (old + 1u == epoch * gridDim.x) {
;             __hip_atomic_store(bar + 64, epoch, __ATOMIC_RELAXED, __HIP_MEMORY_SCOPE_AGENT);
;         } else {
;             while (__hip_atomic_load(bar + 64, __ATOMIC_RELAXED, __HIP_MEMORY_SCOPE_AGENT) < epoch) __builtin_amdgcn_s_sleep(1);
;         }
.LBB0_1048:
	s_or_b64 exec, exec, s[48:49]
	s_add_i32 s2, s82, 9
	s_waitcnt vmcnt(0)
	v_readfirstlane_b32 s3, v1
	s_nop 1
	v_add3_u32 v0, s3, v0, 1
	s_mul_i32 s3, s2, s45
	v_cmp_ne_u32_e32 vcc, s3, v0
	s_and_saveexec_b64 s[38:39], vcc
	s_xor_b64 s[46:47], exec, s[38:39]
	v_readlane_b32 s38, v254, 35
	v_readlane_b32 s39, v254, 36
	s_cbranch_execz .LBB0_1051
	s_nop 3
	v_readlane_b32 vcc_lo, v253, 0
	s_and_b32 vcc_lo, vcc_lo, 31
	s_lshl_b32 vcc_lo, vcc_lo, 6
	s_addk_i32 vcc_lo, 0x1400
	v_mov_b32_e32 v1, vcc_lo
	global_load_dword v0, v1, s[38:39] sc1
	s_waitcnt vmcnt(0)
	v_cmp_le_u32_e32 vcc, s2, v0
	s_cbranch_vccnz .LBB0_1051

; __device__ __forceinline__ void grid_barrier(unsigned* bar, unsigned& epoch) {
;     ...
;         const unsigned old = __hip_atomic_fetch_add(bar, 1u, __ATOMIC_RELAXED, __HIP_MEMORY_SCOPE_AGENT);
;         if (old + 1u == epoch * gridDim.x) {
;             __hip_atomic_store(bar + 64, epoch, __ATOMIC_RELAXED, __HIP_MEMORY_SCOPE_AGENT);
;         } else {
;             while (__hip_atomic_load(bar + 64, __ATOMIC_RELAXED, __HIP_MEMORY_SCOPE_AGENT) < epoch) __builtin_amdgcn_s_sleep(1);
;         }
.LBB0_1116:
	s_or_b64 exec, exec, s[42:43]
	s_waitcnt vmcnt(0)
	v_readfirstlane_b32 s2, v1
	s_nop 1
	v_add3_u32 v0, s2, v0, 1
	s_mul_i32 s2, s18, s45
	v_cmp_ne_u32_e32 vcc, s2, v0
	s_and_saveexec_b64 s[2:3], vcc
	s_xor_b64 s[6:7], exec, s[2:3]
	v_readlane_b32 s2, v254, 35
	v_readlane_b32 s3, v254, 36
	s_cbranch_execz .LBB0_1119
	s_nop 3
	v_readlane_b32 vcc_lo, v253, 0
	s_and_b32 vcc_lo, vcc_lo, 31
	s_lshl_b32 vcc_lo, vcc_lo, 6
	s_addk_i32 vcc_lo, 0x1400
	v_mov_b32_e32 v1, vcc_lo
	global_load_dword v0, v1, s[2:3] sc1
	s_waitcnt vmcnt(0)
	v_cmp_le_u32_e32 vcc, s18, v0
	s_cbranch_vccnz .LBB0_1119
.LBB0_1118:
	global_load_dword v0, v1, s[2:3] sc1
	s_waitcnt vmcnt(0)
	v_cmp_gt_u32_e32 vcc, s18, v0
	s_cbranch_vccnz .LBB0_1118
.LBB0_1119:
	s_andn2_saveexec_b64 s[6:7], s[6:7]
	s_cbranch_execz .LBB0_1121
	v_readlane_b32 s2, v254, 35
	v_mov_b32_e32 v0, s18
	v_readlane_b32 s3, v254, 36
	s_nop 4
	v_mov_b32_e32 v1, 0x1400
	global_store_dword v1, v0, s[2:3] sc1
	global_store_dword v1, v0, s[2:3] offset:64 sc1
	global_store_dword v1, v0, s[2:3] offset:128 sc1
	global_store_dword v1, v0, s[2:3] offset:192 sc1
	global_store_dword v1, v0, s[2:3] offset:256 sc1
	global_store_dword v1, v0, s[2:3] offset:320 sc1
	global_store_dword v1, v0, s[2:3] offset:384 sc1
	global_store_dword v1, v0, s[2:3] offset:448 sc1
	global_store_dword v1, v0, s[2:3] offset:512 sc1
	global_store_dword v1, v0, s[2:3] offset:576 sc1
	global_store_dword v1, v0, s[2:3] offset:640 sc1
	global_store_dword v1, v0, s[2:3] offset:704 sc1
	global_store_dword v1, v0, s[2:3] offset:768 sc1
	global_store_dword v1, v0, s[2:3] offset:832 sc1
	global_store_dword v1, v0, s[2:3] offset:896 sc1
	global_store_dword v1, v0, s[2:3] offset:960 sc1
	global_store_dword v1, v0, s[2:3] offset:1024 sc1
	global_store_dword v1, v0, s[2:3] offset:1088 sc1
	global_store_dword v1, v0, s[2:3] offset:1152 sc1
	global_store_dword v1, v0, s[2:3] offset:1216 sc1
	global_store_dword v1, v0, s[2:3] offset:1280 sc1
	global_store_dword v1, v0, s[2:3] offset:1344 sc1
	global_store_dword v1, v0, s[2:3] offset:1408 sc1
	global_store_dword v1, v0, s[2:3] offset:1472 sc1
	global_store_dword v1, v0, s[2:3] offset:1536 sc1
	global_store_dword v1, v0, s[2:3] offset:1600 sc1
	global_store_dword v1, v0, s[2:3] offset:1664 sc1
	global_store_dword v1, v0, s[2:3] offset:1728 sc1
	global_store_dword v1, v0, s[2:3] offset:1792 sc1
	global_store_dword v1, v0, s[2:3] offset:1856 sc1
	global_store_dword v1, v0, s[2:3] offset:1920 sc1
	global_store_dword v1, v0, s[2:3] offset:1984 sc1

; __device__ __forceinline__ void grid_barrier(unsigned* bar, unsigned& epoch) {
;     ...
;         const unsigned old = __hip_atomic_fetch_add(bar, 1u, __ATOMIC_RELAXED, __HIP_MEMORY_SCOPE_AGENT);
;         if (old + 1u == epoch * gridDim.x) {
;             __hip_atomic_store(bar + 64, epoch, __ATOMIC_RELAXED, __HIP_MEMORY_SCOPE_AGENT);
;         } else {
;             while (__hip_atomic_load(bar + 64, __ATOMIC_RELAXED, __HIP_MEMORY_SCOPE_AGENT) < epoch) __builtin_amdgcn_s_sleep(1);
;         }
.LBB0_1402:
	s_or_b64 exec, exec, s[6:7]
	s_waitcnt vmcnt(0)
	v_readfirstlane_b32 s4, v1
	s_nop 1
	v_add3_u32 v0, s4, v0, 1
	s_mul_i32 s4, s18, s45
	v_cmp_ne_u32_e32 vcc, s4, v0
	s_and_saveexec_b64 s[4:5], vcc
	v_readlane_b32 s22, v254, 35
	s_xor_b64 s[4:5], exec, s[4:5]
	v_readlane_b32 s23, v254, 36
	s_cbranch_execz .LBB0_1405
	s_nop 3
	v_readlane_b32 vcc_lo, v253, 0
	s_and_b32 vcc_lo, vcc_lo, 31
	s_lshl_b32 vcc_lo, vcc_lo, 6
	s_addk_i32 vcc_lo, 0x1400
	v_mov_b32_e32 v1, vcc_lo
	global_load_dword v0, v1, s[22:23] sc1
	s_waitcnt vmcnt(0)
	v_cmp_le_u32_e32 vcc, s18, v0
	s_cbranch_vccnz .LBB0_1405
.LBB0_1404:
	global_load_dword v0, v1, s[22:23] sc1
	s_waitcnt vmcnt(0)
	v_cmp_gt_u32_e32 vcc, s18, v0
	s_cbranch_vccnz .LBB0_1404
.LBB0_1405:
	s_andn2_saveexec_b64 s[4:5], s[4:5]
	s_cbranch_execz .LBB0_1397
	v_readlane_b32 s6, v254, 35
	v_mov_b32_e32 v0, s18
	v_readlane_b32 s7, v254, 36
	s_nop 4
	v_mov_b32_e32 v1, 0x1400
	global_store_dword v1, v0, s[6:7] sc1
	global_store_dword v1, v0, s[6:7] offset:64 sc1
	global_store_dword v1, v0, s[6:7] offset:128 sc1
	global_store_dword v1, v0, s[6:7] offset:192 sc1
	global_store_dword v1, v0, s[6:7] offset:256 sc1
	global_store_dword v1, v0, s[6:7] offset:320 sc1
	global_store_dword v1, v0, s[6:7] offset:384 sc1
	global_store_dword v1, v0, s[6:7] offset:448 sc1
	global_store_dword v1, v0, s[6:7] offset:512 sc1
	global_store_dword v1, v0, s[6:7] offset:576 sc1
	global_store_dword v1, v0, s[6:7] offset:640 sc1
	global_store_dword v1, v0, s[6:7] offset:704 sc1
	global_store_dword v1, v0, s[6:7] offset:768 sc1
	global_store_dword v1, v0, s[6:7] offset:832 sc1
	global_store_dword v1, v0, s[6:7] offset:896 sc1
	global_store_dword v1, v0, s[6:7] offset:960 sc1
	global_store_dword v1, v0, s[6:7] offset:1024 sc1
	global_store_dword v1, v0, s[6:7] offset:1088 sc1
	global_store_dword v1, v0, s[6:7] offset:1152 sc1
	global_store_dword v1, v0, s[6:7] offset:1216 sc1
	global_store_dword v1, v0, s[6:7] offset:1280 sc1
	global_store_dword v1, v0, s[6:7] offset:1344 sc1
	global_store_dword v1, v0, s[6:7] offset:1408 sc1
	global_store_dword v1, v0, s[6:7] offset:1472 sc1
	global_store_dword v1, v0, s[6:7] offset:1536 sc1
	global_store_dword v1, v0, s[6:7] offset:1600 sc1
	global_store_dword v1, v0, s[6:7] offset:1664 sc1
	global_store_dword v1, v0, s[6:7] offset:1728 sc1
	global_store_dword v1, v0, s[6:7] offset:1792 sc1
	global_store_dword v1, v0, s[6:7] offset:1856 sc1
	global_store_dword v1, v0, s[6:7] offset:1920 sc1
	global_store_dword v1, v0, s[6:7] offset:1984 sc1
	s_branch .LBB0_1397

; __device__ __forceinline__ void grid_barrier(unsigned* bar, unsigned& epoch) {
;     ...
;         const unsigned old = __hip_atomic_fetch_add(bar, 1u, __ATOMIC_RELAXED, __HIP_MEMORY_SCOPE_AGENT);
;         if (old + 1u == epoch * gridDim.x) {
;             __hip_atomic_store(bar + 64, epoch, __ATOMIC_RELAXED, __HIP_MEMORY_SCOPE_AGENT);
;         } else {
;             while (__hip_atomic_load(bar + 64, __ATOMIC_RELAXED, __HIP_MEMORY_SCOPE_AGENT) < epoch) __builtin_amdgcn_s_sleep(1);
;         }
.LBB0_1412:
	s_or_b64 exec, exec, s[6:7]
	s_waitcnt vmcnt(0)
	v_readfirstlane_b32 s4, v1
	s_nop 1
	v_add3_u32 v0, s4, v0, 1
	s_mul_i32 s4, s82, s45
	v_cmp_ne_u32_e32 vcc, s4, v0
	s_and_saveexec_b64 s[4:5], vcc
	v_readlane_b32 s8, v254, 35
	s_xor_b64 s[4:5], exec, s[4:5]
	v_readlane_b32 s9, v254, 36
	s_cbranch_execz .LBB0_1415
	s_nop 3
	v_readlane_b32 vcc_lo, v253, 0
	s_and_b32 vcc_lo, vcc_lo, 31
	s_lshl_b32 vcc_lo, vcc_lo, 6
	s_addk_i32 vcc_lo, 0x1400
	v_mov_b32_e32 v1, vcc_lo
	global_load_dword v0, v1, s[8:9] sc1
	s_waitcnt vmcnt(0)
	v_cmp_le_u32_e32 vcc, s82, v0
	s_cbranch_vccnz .LBB0_1415
.LBB0_1414:
	global_load_dword v0, v1, s[8:9] sc1
	s_waitcnt vmcnt(0)
	v_cmp_gt_u32_e32 vcc, s82, v0
	s_cbranch_vccnz .LBB0_1414

; __device__ __forceinline__ void grid_barrier(unsigned* bar, unsigned& epoch) {
;     ...
;         if (old + 1u == epoch * gridDim.x) {
;             __hip_atomic_store(bar + 64, epoch, __ATOMIC_RELAXED, __HIP_MEMORY_SCOPE_AGENT);
.LBB0_1416:
	v_readlane_b32 s6, v254, 35
	v_mov_b32_e32 v0, s82
	v_readlane_b32 s7, v254, 36
	s_nop 4
	v_mov_b32_e32 v1, 0x1400
	global_store_dword v1, v0, s[6:7] sc1
	global_store_dword v1, v0, s[6:7] offset:64 sc1
	global_store_dword v1, v0, s[6:7] offset:128 sc1
	global_store_dword v1, v0, s[6:7] offset:192 sc1
	global_store_dword v1, v0, s[6:7] offset:256 sc1
	global_store_dword v1, v0, s[6:7] offset:320 sc1
	global_store_dword v1, v0, s[6:7] offset:384 sc1
	global_store_dword v1, v0, s[6:7] offset:448 sc1
	global_store_dword v1, v0, s[6:7] offset:512 sc1
	global_store_dword v1, v0, s[6:7] offset:576 sc1
	global_store_dword v1, v0, s[6:7] offset:640 sc1
	global_store_dword v1, v0, s[6:7] offset:704 sc1
	global_store_dword v1, v0, s[6:7] offset:768 sc1
	global_store_dword v1, v0, s[6:7] offset:832 sc1
	global_store_dword v1, v0, s[6:7] offset:896 sc1
	global_store_dword v1, v0, s[6:7] offset:960 sc1
	global_store_dword v1, v0, s[6:7] offset:1024 sc1
	global_store_dword v1, v0, s[6:7] offset:1088 sc1
	global_store_dword v1, v0, s[6:7] offset:1152 sc1
	global_store_dword v1, v0, s[6:7] offset:1216 sc1
	global_store_dword v1, v0, s[6:7] offset:1280 sc1
	global_store_dword v1, v0, s[6:7] offset:1344 sc1
	global_store_dword v1, v0, s[6:7] offset:1408 sc1
	global_store_dword v1, v0, s[6:7] offset:1472 sc1
	global_store_dword v1, v0, s[6:7] offset:1536 sc1
	global_store_dword v1, v0, s[6:7] offset:1600 sc1
	global_store_dword v1, v0, s[6:7] offset:1664 sc1
	global_store_dword v1, v0, s[6:7] offset:1728 sc1
	global_store_dword v1, v0, s[6:7] offset:1792 sc1
	global_store_dword v1, v0, s[6:7] offset:1856 sc1
	global_store_dword v1, v0, s[6:7] offset:1920 sc1
	global_store_dword v1, v0, s[6:7] offset:1984 sc1
	s_getpc_b64 s[98:99]
